# attention epilogue rewritten: O*inv transposed through wave-private LDS, gate loads and output stores as dwordx4 instead of 64+64 ushort ops per lane
# speedup vs baseline: 1.0005x; 1.0005x over previous
.LBB0_687:
	s_or_b64 exec, exec, s[8:9]
	s_add_i32 s10, s10, 1
	s_add_i32 s13, s13, 32
	s_add_i32 s12, s12, 1
	s_add_i32 s11, s11, 1
	ds_read_b128 v[0:3], v170
	s_waitcnt lgkmcnt(0)
	v_mul_f32_e32 v82, v82, v0
	v_mul_f32_e32 v66, v66, v0
	v_mul_f32_e32 v50, v50, v0
	v_mul_f32_e32 v34, v34, v0
	v_mul_f32_e32 v83, v83, v1
	v_mul_f32_e32 v67, v67, v1
	v_mul_f32_e32 v51, v51, v1
	v_mul_f32_e32 v35, v35, v1
	v_mul_f32_e32 v84, v84, v2
	v_mul_f32_e32 v68, v68, v2
	v_mul_f32_e32 v52, v52, v2
	v_mul_f32_e32 v36, v36, v2
	v_mul_f32_e32 v85, v85, v3
	v_mul_f32_e32 v69, v69, v3
	v_mul_f32_e32 v53, v53, v3
	v_mul_f32_e32 v37, v37, v3
	ds_write_b32 v24, v82
	ds_write_b32 v24, v66 offset:128
	ds_write_b32 v24, v50 offset:256
	ds_write_b32 v24, v34 offset:384
	ds_write_b32 v24, v83 offset:528
	ds_write_b32 v24, v67 offset:656
	ds_write_b32 v24, v51 offset:784
	ds_write_b32 v24, v35 offset:912
	ds_write_b32 v24, v84 offset:1056
	ds_write_b32 v24, v68 offset:1184
	ds_write_b32 v24, v52 offset:1312
	ds_write_b32 v24, v36 offset:1440
	ds_write_b32 v24, v85 offset:1584
	ds_write_b32 v24, v69 offset:1712
	ds_write_b32 v24, v53 offset:1840
	ds_write_b32 v24, v37 offset:1968
	s_waitcnt lgkmcnt(0)
	ds_read_b128 v[8:11], v25
	ds_read_b128 v[12:15], v25 offset:16
	ds_read_b128 v[16:19], v25 offset:2112
	ds_read_b128 v[20:23], v25 offset:2128
	s_waitcnt vmcnt(6)
	v_lshlrev_b32_e32 v234, 16, v98
	v_and_b32_e32 v235, 0xffff0000, v98
	v_lshlrev_b32_e32 v236, 16, v99
	v_and_b32_e32 v237, 0xffff0000, v99
	v_lshlrev_b32_e32 v238, 16, v100
	v_and_b32_e32 v239, 0xffff0000, v100
	v_lshlrev_b32_e32 v240, 16, v101
	v_and_b32_e32 v241, 0xffff0000, v101
	s_waitcnt lgkmcnt(2)
	v_mul_f32_e32 v234, v8, v234
	v_mul_f32_e32 v235, v9, v235
	v_mul_f32_e32 v236, v10, v236
	v_mul_f32_e32 v237, v11, v237
	v_mul_f32_e32 v238, v12, v238
	v_mul_f32_e32 v239, v13, v239
	v_mul_f32_e32 v240, v14, v240
	v_mul_f32_e32 v241, v15, v241
	v_cvt_pk_bf16_f32 v28, v234, v235
	v_cvt_pk_bf16_f32 v29, v236, v237
	v_cvt_pk_bf16_f32 v30, v238, v239
	v_cvt_pk_bf16_f32 v31, v240, v241
	global_store_dwordx4 v26, v[28:31], s[50:51]
	v_add_u32_e32 v27, 0x4000, v26
	v_lshlrev_b32_e32 v234, 16, v102
	v_and_b32_e32 v235, 0xffff0000, v102
	v_lshlrev_b32_e32 v236, 16, v103
	v_and_b32_e32 v237, 0xffff0000, v103
	v_lshlrev_b32_e32 v238, 16, v104
	v_and_b32_e32 v239, 0xffff0000, v104
	v_lshlrev_b32_e32 v240, 16, v105
	v_and_b32_e32 v241, 0xffff0000, v105
	s_waitcnt lgkmcnt(0)
	v_mul_f32_e32 v234, v16, v234
	v_mul_f32_e32 v235, v17, v235
	v_mul_f32_e32 v236, v18, v236
	v_mul_f32_e32 v237, v19, v237
	v_mul_f32_e32 v238, v20, v238
	v_mul_f32_e32 v239, v21, v239
	v_mul_f32_e32 v240, v22, v240
	v_mul_f32_e32 v241, v23, v241
	v_cvt_pk_bf16_f32 v242, v234, v235
	v_cvt_pk_bf16_f32 v243, v236, v237
	v_cvt_pk_bf16_f32 v244, v238, v239
	v_cvt_pk_bf16_f32 v245, v240, v241
	global_store_dwordx4 v27, v[242:245], s[50:51]
	v_add_u32_e32 v26, 0x4000, v27
	ds_read_b128 v[0:3], v170 offset:32
	s_waitcnt lgkmcnt(0)
	v_mul_f32_e32 v86, v86, v0
	v_mul_f32_e32 v70, v70, v0
	v_mul_f32_e32 v54, v54, v0
	v_mul_f32_e32 v38, v38, v0
	v_mul_f32_e32 v87, v87, v1
	v_mul_f32_e32 v71, v71, v1
	v_mul_f32_e32 v55, v55, v1
	v_mul_f32_e32 v39, v39, v1
	v_mul_f32_e32 v88, v88, v2
	v_mul_f32_e32 v72, v72, v2
	v_mul_f32_e32 v56, v56, v2
	v_mul_f32_e32 v40, v40, v2
	v_mul_f32_e32 v89, v89, v3
	v_mul_f32_e32 v73, v73, v3
	v_mul_f32_e32 v57, v57, v3
	v_mul_f32_e32 v41, v41, v3
	ds_write_b32 v24, v86
	ds_write_b32 v24, v70 offset:128
	ds_write_b32 v24, v54 offset:256
	ds_write_b32 v24, v38 offset:384
	ds_write_b32 v24, v87 offset:528
	ds_write_b32 v24, v71 offset:656
	ds_write_b32 v24, v55 offset:784
	ds_write_b32 v24, v39 offset:912
	ds_write_b32 v24, v88 offset:1056
	ds_write_b32 v24, v72 offset:1184
	ds_write_b32 v24, v56 offset:1312
	ds_write_b32 v24, v40 offset:1440
	ds_write_b32 v24, v89 offset:1584
	ds_write_b32 v24, v73 offset:1712
	ds_write_b32 v24, v57 offset:1840
	ds_write_b32 v24, v41 offset:1968
	s_waitcnt lgkmcnt(0)
	ds_read_b128 v[8:11], v25
	ds_read_b128 v[12:15], v25 offset:16
	ds_read_b128 v[16:19], v25 offset:2112
	ds_read_b128 v[20:23], v25 offset:2128
	s_waitcnt vmcnt(6)
	v_lshlrev_b32_e32 v234, 16, v106
	v_and_b32_e32 v235, 0xffff0000, v106
	v_lshlrev_b32_e32 v236, 16, v107
	v_and_b32_e32 v237, 0xffff0000, v107
	v_lshlrev_b32_e32 v238, 16, v108
	v_and_b32_e32 v239, 0xffff0000, v108
	v_lshlrev_b32_e32 v240, 16, v109
	v_and_b32_e32 v241, 0xffff0000, v109
	s_waitcnt lgkmcnt(2)
	v_mul_f32_e32 v234, v8, v234
	v_mul_f32_e32 v235, v9, v235
	v_mul_f32_e32 v236, v10, v236
	v_mul_f32_e32 v237, v11, v237
	v_mul_f32_e32 v238, v12, v238
	v_mul_f32_e32 v239, v13, v239
	v_mul_f32_e32 v240, v14, v240
	v_mul_f32_e32 v241, v15, v241
	v_cvt_pk_bf16_f32 v28, v234, v235
	v_cvt_pk_bf16_f32 v29, v236, v237
	v_cvt_pk_bf16_f32 v30, v238, v239
	v_cvt_pk_bf16_f32 v31, v240, v241
	global_store_dwordx4 v26, v[28:31], s[50:51]
	v_add_u32_e32 v27, 0x4000, v26
	v_lshlrev_b32_e32 v234, 16, v110
	v_and_b32_e32 v235, 0xffff0000, v110
	v_lshlrev_b32_e32 v236, 16, v111
	v_and_b32_e32 v237, 0xffff0000, v111
	v_lshlrev_b32_e32 v238, 16, v112
	v_and_b32_e32 v239, 0xffff0000, v112
	v_lshlrev_b32_e32 v240, 16, v113
	v_and_b32_e32 v241, 0xffff0000, v113
	s_waitcnt lgkmcnt(0)
	v_mul_f32_e32 v234, v16, v234
	v_mul_f32_e32 v235, v17, v235
	v_mul_f32_e32 v236, v18, v236
	v_mul_f32_e32 v237, v19, v237
	v_mul_f32_e32 v238, v20, v238
	v_mul_f32_e32 v239, v21, v239
	v_mul_f32_e32 v240, v22, v240
	v_mul_f32_e32 v241, v23, v241
	v_cvt_pk_bf16_f32 v242, v234, v235
	v_cvt_pk_bf16_f32 v243, v236, v237
	v_cvt_pk_bf16_f32 v244, v238, v239
	v_cvt_pk_bf16_f32 v245, v240, v241
	global_store_dwordx4 v27, v[242:245], s[50:51]
	v_add_u32_e32 v26, 0x4000, v27
	ds_read_b128 v[0:3], v170 offset:64
	s_waitcnt lgkmcnt(0)
	v_mul_f32_e32 v90, v90, v0
	v_mul_f32_e32 v74, v74, v0
	v_mul_f32_e32 v58, v58, v0
	v_mul_f32_e32 v42, v42, v0
	v_mul_f32_e32 v91, v91, v1
	v_mul_f32_e32 v75, v75, v1
	v_mul_f32_e32 v59, v59, v1
	v_mul_f32_e32 v43, v43, v1
	v_mul_f32_e32 v92, v92, v2
	v_mul_f32_e32 v76, v76, v2
	v_mul_f32_e32 v60, v60, v2
	v_mul_f32_e32 v44, v44, v2
	v_mul_f32_e32 v93, v93, v3
	v_mul_f32_e32 v77, v77, v3
	v_mul_f32_e32 v61, v61, v3
	v_mul_f32_e32 v45, v45, v3
	ds_write_b32 v24, v90
	ds_write_b32 v24, v74 offset:128
	ds_write_b32 v24, v58 offset:256
	ds_write_b32 v24, v42 offset:384
	ds_write_b32 v24, v91 offset:528
	ds_write_b32 v24, v75 offset:656
	ds_write_b32 v24, v59 offset:784
	ds_write_b32 v24, v43 offset:912
	ds_write_b32 v24, v92 offset:1056
	ds_write_b32 v24, v76 offset:1184
	ds_write_b32 v24, v60 offset:1312
	ds_write_b32 v24, v44 offset:1440
	ds_write_b32 v24, v93 offset:1584
	ds_write_b32 v24, v77 offset:1712
	ds_write_b32 v24, v61 offset:1840
	ds_write_b32 v24, v45 offset:1968
	s_waitcnt lgkmcnt(0)
	ds_read_b128 v[8:11], v25
	ds_read_b128 v[12:15], v25 offset:16
	ds_read_b128 v[16:19], v25 offset:2112
	ds_read_b128 v[20:23], v25 offset:2128
	s_waitcnt vmcnt(6)
	v_lshlrev_b32_e32 v234, 16, v114
	v_and_b32_e32 v235, 0xffff0000, v114
	v_lshlrev_b32_e32 v236, 16, v115
	v_and_b32_e32 v237, 0xffff0000, v115
	v_lshlrev_b32_e32 v238, 16, v116
	v_and_b32_e32 v239, 0xffff0000, v116
	v_lshlrev_b32_e32 v240, 16, v117
	v_and_b32_e32 v241, 0xffff0000, v117
	s_waitcnt lgkmcnt(2)
	v_mul_f32_e32 v234, v8, v234
	v_mul_f32_e32 v235, v9, v235
	v_mul_f32_e32 v236, v10, v236
	v_mul_f32_e32 v237, v11, v237
	v_mul_f32_e32 v238, v12, v238
	v_mul_f32_e32 v239, v13, v239
	v_mul_f32_e32 v240, v14, v240
	v_mul_f32_e32 v241, v15, v241
	v_cvt_pk_bf16_f32 v28, v234, v235
	v_cvt_pk_bf16_f32 v29, v236, v237
	v_cvt_pk_bf16_f32 v30, v238, v239
	v_cvt_pk_bf16_f32 v31, v240, v241
	global_store_dwordx4 v26, v[28:31], s[50:51]
	v_add_u32_e32 v27, 0x4000, v26
	v_lshlrev_b32_e32 v234, 16, v118
	v_and_b32_e32 v235, 0xffff0000, v118
	v_lshlrev_b32_e32 v236, 16, v119
	v_and_b32_e32 v237, 0xffff0000, v119
	v_lshlrev_b32_e32 v238, 16, v120
	v_and_b32_e32 v239, 0xffff0000, v120
	v_lshlrev_b32_e32 v240, 16, v121
	v_and_b32_e32 v241, 0xffff0000, v121
	s_waitcnt lgkmcnt(0)
	v_mul_f32_e32 v234, v16, v234
	v_mul_f32_e32 v235, v17, v235
	v_mul_f32_e32 v236, v18, v236
	v_mul_f32_e32 v237, v19, v237
	v_mul_f32_e32 v238, v20, v238
	v_mul_f32_e32 v239, v21, v239
	v_mul_f32_e32 v240, v22, v240
	v_mul_f32_e32 v241, v23, v241
	v_cvt_pk_bf16_f32 v242, v234, v235
	v_cvt_pk_bf16_f32 v243, v236, v237
	v_cvt_pk_bf16_f32 v244, v238, v239
	v_cvt_pk_bf16_f32 v245, v240, v241
	global_store_dwordx4 v27, v[242:245], s[50:51]
	v_add_u32_e32 v26, 0x4000, v27
	ds_read_b128 v[0:3], v170 offset:96
	s_waitcnt lgkmcnt(0)
	v_mul_f32_e32 v94, v94, v0
	v_mul_f32_e32 v78, v78, v0
	v_mul_f32_e32 v62, v62, v0
	v_mul_f32_e32 v46, v46, v0
	v_mul_f32_e32 v95, v95, v1
	v_mul_f32_e32 v79, v79, v1
	v_mul_f32_e32 v63, v63, v1
	v_mul_f32_e32 v47, v47, v1
	v_mul_f32_e32 v96, v96, v2
	v_mul_f32_e32 v80, v80, v2
	v_mul_f32_e32 v64, v64, v2
	v_mul_f32_e32 v48, v48, v2
	v_mul_f32_e32 v97, v97, v3
	v_mul_f32_e32 v81, v81, v3
	v_mul_f32_e32 v65, v65, v3
	v_mul_f32_e32 v49, v49, v3
	ds_write_b32 v24, v94
	ds_write_b32 v24, v78 offset:128
	ds_write_b32 v24, v62 offset:256
	ds_write_b32 v24, v46 offset:384
	ds_write_b32 v24, v95 offset:528
	ds_write_b32 v24, v79 offset:656
	ds_write_b32 v24, v63 offset:784
	ds_write_b32 v24, v47 offset:912
	ds_write_b32 v24, v96 offset:1056
	ds_write_b32 v24, v80 offset:1184
	ds_write_b32 v24, v64 offset:1312
	ds_write_b32 v24, v48 offset:1440
	ds_write_b32 v24, v97 offset:1584
	ds_write_b32 v24, v81 offset:1712
	ds_write_b32 v24, v65 offset:1840
	ds_write_b32 v24, v49 offset:1968
	s_waitcnt lgkmcnt(0)
	ds_read_b128 v[8:11], v25
	ds_read_b128 v[12:15], v25 offset:16
	ds_read_b128 v[16:19], v25 offset:2112
	ds_read_b128 v[20:23], v25 offset:2128
	s_waitcnt vmcnt(6)
	v_lshlrev_b32_e32 v234, 16, v122
	v_and_b32_e32 v235, 0xffff0000, v122
	v_lshlrev_b32_e32 v236, 16, v123
	v_and_b32_e32 v237, 0xffff0000, v123
	v_lshlrev_b32_e32 v238, 16, v124
	v_and_b32_e32 v239, 0xffff0000, v124
	v_lshlrev_b32_e32 v240, 16, v125
	v_and_b32_e32 v241, 0xffff0000, v125
	s_waitcnt lgkmcnt(2)
	v_mul_f32_e32 v234, v8, v234
	v_mul_f32_e32 v235, v9, v235
	v_mul_f32_e32 v236, v10, v236
	v_mul_f32_e32 v237, v11, v237
	v_mul_f32_e32 v238, v12, v238
	v_mul_f32_e32 v239, v13, v239
	v_mul_f32_e32 v240, v14, v240
	v_mul_f32_e32 v241, v15, v241
	v_cvt_pk_bf16_f32 v28, v234, v235
	v_cvt_pk_bf16_f32 v29, v236, v237
	v_cvt_pk_bf16_f32 v30, v238, v239
	v_cvt_pk_bf16_f32 v31, v240, v241
	global_store_dwordx4 v26, v[28:31], s[50:51]
	v_add_u32_e32 v27, 0x4000, v26
	v_lshlrev_b32_e32 v234, 16, v126
	v_and_b32_e32 v235, 0xffff0000, v126
	v_lshlrev_b32_e32 v236, 16, v127
	v_and_b32_e32 v237, 0xffff0000, v127
	v_lshlrev_b32_e32 v238, 16, v128
	v_and_b32_e32 v239, 0xffff0000, v128
	v_lshlrev_b32_e32 v240, 16, v129
	v_and_b32_e32 v241, 0xffff0000, v129
	s_waitcnt lgkmcnt(0)
	v_mul_f32_e32 v234, v16, v234
	v_mul_f32_e32 v235, v17, v235
	v_mul_f32_e32 v236, v18, v236
	v_mul_f32_e32 v237, v19, v237
	v_mul_f32_e32 v238, v20, v238
	v_mul_f32_e32 v239, v21, v239
	v_mul_f32_e32 v240, v22, v240
	v_mul_f32_e32 v241, v23, v241
	v_cvt_pk_bf16_f32 v242, v234, v235
	v_cvt_pk_bf16_f32 v243, v236, v237
	v_cvt_pk_bf16_f32 v244, v238, v239
	v_cvt_pk_bf16_f32 v245, v240, v241
	global_store_dwordx4 v27, v[242:245], s[50:51]
	v_add_u32_e32 v26, 0x4000, v27
	v_readlane_b32 s8, v255, 11
	s_cmp_eq_u32 s10, s8
	s_cselect_b64 s[8:9], -1, 0
	v_mov_b32_e32 v159, v33

.LBB0_705:
	ds_bpermute_b32 v0, v147, v209
	v_lshrrev_b32_e32 v11, 4, v146
	v_lshrrev_b32_e32 v12, 1, v168
	v_add_u32_e32 v11, v11, v12
	v_and_b32_e32 v13, 15, v146
	v_add_u32_e32 v14, v159, v11
	v_mul_lo_u32 v15, v14, s97
	v_lshlrev_b32_e32 v16, 4, v13
	v_lshl_add_u32 v16, v160, 1, v16
	s_movk_i32 s14, 0x1400
	s_mov_b32 s15, 0xb000
	v_add3_u32 v130, v15, v16, s14
	v_add_u32_e32 v131, s15, v130
	v_add_u32_e32 v132, s15, v131
	v_add_u32_e32 v133, s15, v132
	v_add_u32_e32 v134, s15, v133
	v_add_u32_e32 v135, s15, v134
	v_add_u32_e32 v136, s15, v135
	v_add_u32_e32 v137, s15, v136
	global_load_dwordx4 v[98:101], v130, s[0:1]
	global_load_dwordx4 v[102:105], v131, s[0:1]
	global_load_dwordx4 v[106:109], v132, s[0:1]
	global_load_dwordx4 v[110:113], v133, s[0:1]
	global_load_dwordx4 v[114:117], v134, s[0:1]
	global_load_dwordx4 v[118:121], v135, s[0:1]
	global_load_dwordx4 v[122:125], v136, s[0:1]
	global_load_dwordx4 v[126:129], v137, s[0:1]
	v_lshl_add_u32 v26, v14, 12, v16
	v_add_u32_e32 v26, 0x55d0400, v26
	v_mul_u32_u24_e32 v8, 0x90, v146
	v_sub_u32_e32 v9, v204, v8
	v_lshlrev_b32_e32 v10, 1, v168
	v_sub_u32_e32 v9, v9, v10
	s_movk_i32 s14, 0x210
	v_mad_u32_u24 v24, v168, s14, v9
	v_lshl_add_u32 v24, v146, 2, v24
	v_mad_u32_u24 v25, v11, s14, v9
	v_lshl_add_u32 v25, v13, 5, v25
	s_and_saveexec_b64 s[8:9], s[4:5]
	s_cbranch_execz .LBB0_687
	v_sub_f32_e32 v1, v157, v206
	v_cmp_gt_f32_e32 vcc, s20, v1
	s_waitcnt lgkmcnt(0)
	v_add_f32_e32 v0, v209, v0
	v_cndmask_b32_e32 v2, 0, v228, vcc
	v_add_f32_e32 v1, v1, v2
	v_exp_f32_e32 v1, v1
	v_cndmask_b32_e32 v2, 0, v223, vcc
	v_ldexp_f32 v1, v1, v2
	v_add_f32_e32 v0, v1, v0
	v_div_scale_f32 v1, s[14:15], v0, v0, 1.0
	v_rcp_f32_e32 v2, v1
	v_div_scale_f32 v3, vcc, 1.0, v0, 1.0
	v_fma_f32 v4, -v1, v2, 1.0
	v_fmac_f32_e32 v2, v4, v2
	v_mul_f32_e32 v4, v3, v2
	v_fma_f32 v5, -v1, v4, v3
	v_fmac_f32_e32 v4, v5, v2
	v_fma_f32 v1, -v1, v4, v3
	v_div_fmas_f32 v1, v1, v2, v4
	v_div_fixup_f32 v0, v1, v0, 1.0
	ds_write_b32 v169, v0
	s_branch .LBB0_687
